# p0a_item_order_kb_fastest
# baseline (speedup 1.0000x reference)
.LBB0_11:
	s_mul_hi_i32 s2, s14, 0x4325c53f
	s_lshr_b32 s3, s2, 31
	s_ashr_i32 s2, s2, 13
	s_add_i32 s8, s2, s3
	s_mul_i32 s2, s8, 0x7a00
	s_sub_i32 s28, s14, s2
	s_mov_b32 s32, 5
	s_cmpk_lt_u32 s28, 0x2a00
	s_cbranch_scc1 .Lp0_kdone
	s_mov_b32 s32, 4
	s_cmpk_lt_u32 s28, 0x2e00
	s_cbranch_scc1 .Lp0_kdone
	s_mov_b32 s32, 3
	s_cmpk_lt_u32 s28, 0x3200
	s_cbranch_scc1 .Lp0_kdone
	s_mov_b32 s32, 5
	s_cmpk_lt_u32 s28, 0x5a00
	s_cbranch_scc1 .Lp0_kdone
	s_mov_b32 s32, 7
.Lp0_kdone:
	s_cmpk_gt_i32 s28, 0x29ff
	s_mov_b64 s[10:11], -1
	s_cbranch_scc0 .LBB0_31
	s_cmpk_gt_u32 s28, 0x2dff
	s_cbranch_scc0 .LBB0_28
	s_cmpk_gt_u32 s28, 0x2fff
	s_cbranch_scc0 .LBB0_25
	s_cmpk_gt_u32 s28, 0x31ff
	s_mov_b64 s[6:7], -1
	s_cbranch_scc0 .LBB0_23
	s_cmpk_gt_u32 s28, 0x39ff
	s_cbranch_scc0 .LBB0_20
	s_ashr_i32 s9, s8, 31
	s_lshl_b64 s[2:3], s[8:9], 26
	s_cmpk_gt_u32 s28, 0x59ff
	s_cbranch_scc0 .LBB0_18
	s_load_dwordx2 s[4:5], s[0:1], 0xb0
	s_add_i32 s29, s28, 0xffffa600
	s_mul_i32 s7, s8, 0x2040000
	s_mul_hi_i32 s6, s8, 0x2040000
	s_waitcnt lgkmcnt(0)
	s_add_u32 s12, s4, s2
	s_addc_u32 s13, s5, s3
	s_add_u32 s4, s16, s7
	s_addc_u32 s5, s17, s6
	s_mov_b64 s[6:7], 0

.LBB0_33:
	s_mov_b32 s3, 1
	s_mov_b32 s11, 0
	s_lshl_b32 s9, 1, s32
	s_add_i32 s9, s9, -1
	s_and_b32 s9, s29, s9
	s_lshr_b32 s8, s29, s32
	s_lshl_b32 s8, s8, 5
	s_lshl_b32 s10, s9, 6
	s_ashr_i32 s9, s8, 31
	s_lshl_b64 s[28:29], s[8:9], 2
	s_add_u32 s12, s12, s28
	s_addc_u32 s13, s13, s29
	v_lshl_add_u64 v[10:11], s[12:13], 0, v[8:9]
	s_mov_b32 s9, s10
	s_mov_b32 s12, s27
	s_mov_b32 s13, 32
